# softmax decision: cross-half row-max combine (permlane32_swap) moved into the rare rescale path
# speedup vs baseline: 1.0083x; 1.0083x over previous
.Lat_loop:
	s_waitcnt lgkmcnt(0)
	v_mfma_f32_32x32x16_bf16 v[96:111], v[48:51], v[136:139], v[32:47]
	ds_read_b64_tr_b16 v[168:169], v146 offset:0
	ds_read_b64_tr_b16 v[170:171], v146 offset:1024
	ds_read_b64_tr_b16 v[172:173], v146 offset:512
	ds_read_b64_tr_b16 v[174:175], v146 offset:1536
	v_mfma_f32_32x32x16_bf16 v[96:111], v[52:55], v[140:143], v[96:111]
	ds_read_b64_tr_b16 v[176:177], v146 offset:2048
	ds_read_b64_tr_b16 v[178:179], v146 offset:3072
	ds_read_b64_tr_b16 v[180:181], v146 offset:2560
	ds_read_b64_tr_b16 v[182:183], v146 offset:3584
	v_mfma_f32_32x32x16_bf16 v[112:127], v[56:59], v[136:139], v[32:47]
	ds_read_b64_tr_b16 v[184:185], v146 offset:4096
	ds_read_b64_tr_b16 v[186:187], v146 offset:5120
	ds_read_b64_tr_b16 v[188:189], v146 offset:4608
	ds_read_b64_tr_b16 v[190:191], v146 offset:5632
	v_mfma_f32_32x32x16_bf16 v[112:127], v[60:63], v[140:143], v[112:127]
	ds_read_b64_tr_b16 v[192:193], v146 offset:6144
	ds_read_b64_tr_b16 v[194:195], v146 offset:7168
	ds_read_b64_tr_b16 v[196:197], v146 offset:6656
	ds_read_b64_tr_b16 v[198:199], v146 offset:7680
	v_max3_f32 v132, v96, v97, v98
	v_max3_f32 v133, v99, v100, v101
	v_max3_f32 v132, v132, v102, v103
	v_max3_f32 v133, v133, v104, v105
	v_max3_f32 v132, v132, v106, v107
	v_max3_f32 v133, v133, v108, v109
	v_max3_f32 v132, v132, v110, v111
	s_nop 1
	v_max3_f32 v133, v133, v112, v113
	v_max3_f32 v132, v132, v114, v115
	v_max3_f32 v133, v133, v116, v117
	v_max3_f32 v132, v132, v118, v119
	v_max3_f32 v133, v133, v120, v121
	v_max3_f32 v132, v132, v122, v123
	v_max3_f32 v133, v133, v124, v125
	v_max3_f32 v132, v132, v126, v127
	v_max_f32_e32 v132, v132, v133
	s_cmp_lg_u32 s94, 0
	s_cbranch_scc1 .Lat_rareg0a
	v_cmp_lt_f32_e32 vcc, s4, v132
	s_cbranch_vccnz .Lat_rareg0a
.Lat_backg0a:
	v_exp_f32_e32 v96, v96
	v_exp_f32_e32 v97, v97
	v_exp_f32_e32 v98, v98
	v_exp_f32_e32 v99, v99
	v_exp_f32_e32 v100, v100
	v_exp_f32_e32 v101, v101
	v_exp_f32_e32 v102, v102
	v_exp_f32_e32 v103, v103
	v_cvt_pk_bf16_f32 v162, v96, v97
	v_cvt_pk_bf16_f32 v163, v98, v99
	v_cvt_pk_bf16_f32 v164, v100, v101
	v_cvt_pk_bf16_f32 v165, v102, v103
	v_pk_add_f32 v[128:129], v[128:129], v[96:97]
	v_pk_add_f32 v[128:129], v[128:129], v[98:99]
	v_pk_add_f32 v[128:129], v[128:129], v[100:101]
	v_pk_add_f32 v[128:129], v[128:129], v[102:103]
	s_waitcnt lgkmcnt(12)
	v_mfma_f32_32x32x16_bf16 v[0:15], v[162:165], v[168:171], v[0:15]
	v_exp_f32_e32 v104, v104
	v_exp_f32_e32 v105, v105
	v_exp_f32_e32 v106, v106
	v_exp_f32_e32 v107, v107
	v_mfma_f32_32x32x16_bf16 v[16:31], v[162:165], v[172:175], v[16:31]
	v_exp_f32_e32 v108, v108
	v_exp_f32_e32 v109, v109
	v_exp_f32_e32 v110, v110
	v_exp_f32_e32 v111, v111
	v_cvt_pk_bf16_f32 v162, v104, v105
	v_cvt_pk_bf16_f32 v163, v106, v107
	v_cvt_pk_bf16_f32 v164, v108, v109
	v_cvt_pk_bf16_f32 v165, v110, v111
	v_pk_add_f32 v[128:129], v[128:129], v[104:105]
	v_pk_add_f32 v[128:129], v[128:129], v[106:107]
	v_pk_add_f32 v[128:129], v[128:129], v[108:109]
	v_pk_add_f32 v[128:129], v[128:129], v[110:111]
	s_waitcnt lgkmcnt(8)
	v_mfma_f32_32x32x16_bf16 v[0:15], v[162:165], v[176:179], v[0:15]
	v_exp_f32_e32 v112, v112
	v_exp_f32_e32 v113, v113
	v_exp_f32_e32 v114, v114
	v_exp_f32_e32 v115, v115
	v_mfma_f32_32x32x16_bf16 v[16:31], v[162:165], v[180:183], v[16:31]
	v_mfma_f32_32x32x16_bf16 v[96:111], v[48:51], v[150:153], v[64:79]
	v_exp_f32_e32 v116, v116
	v_exp_f32_e32 v117, v117
	v_exp_f32_e32 v118, v118
	v_exp_f32_e32 v119, v119
	v_mfma_f32_32x32x16_bf16 v[96:111], v[52:55], v[154:157], v[96:111]
	v_cvt_pk_bf16_f32 v162, v112, v113
	v_cvt_pk_bf16_f32 v163, v114, v115
	v_cvt_pk_bf16_f32 v164, v116, v117
	v_cvt_pk_bf16_f32 v165, v118, v119
	v_pk_add_f32 v[128:129], v[128:129], v[112:113]
	v_pk_add_f32 v[128:129], v[128:129], v[114:115]
	v_pk_add_f32 v[128:129], v[128:129], v[116:117]
	v_pk_add_f32 v[128:129], v[128:129], v[118:119]
	s_waitcnt lgkmcnt(4)
	v_mfma_f32_32x32x16_bf16 v[0:15], v[162:165], v[184:187], v[0:15]
	v_exp_f32_e32 v120, v120
	v_exp_f32_e32 v121, v121
	v_exp_f32_e32 v122, v122
	v_exp_f32_e32 v123, v123
	v_mfma_f32_32x32x16_bf16 v[16:31], v[162:165], v[188:191], v[16:31]
	v_exp_f32_e32 v124, v124
	v_exp_f32_e32 v125, v125
	v_exp_f32_e32 v126, v126
	v_exp_f32_e32 v127, v127
	v_cvt_pk_bf16_f32 v162, v120, v121
	v_cvt_pk_bf16_f32 v163, v122, v123
	v_cvt_pk_bf16_f32 v164, v124, v125
	v_cvt_pk_bf16_f32 v165, v126, v127
	v_pk_add_f32 v[128:129], v[128:129], v[120:121]
	v_pk_add_f32 v[128:129], v[128:129], v[122:123]
	v_pk_add_f32 v[128:129], v[128:129], v[124:125]
	v_pk_add_f32 v[128:129], v[128:129], v[126:127]
	v_mfma_f32_32x32x16_bf16 v[112:127], v[56:59], v[150:153], v[64:79]
	v_mfma_f32_32x32x16_bf16 v[112:127], v[60:63], v[154:157], v[112:127]
	s_waitcnt lgkmcnt(0)
	v_mfma_f32_32x32x16_bf16 v[0:15], v[162:165], v[192:195], v[0:15]
	v_max3_f32 v132, v96, v97, v98
	v_max3_f32 v133, v99, v100, v101
	v_max3_f32 v132, v132, v102, v103
	v_max3_f32 v133, v133, v104, v105
	v_max3_f32 v132, v132, v106, v107
	v_max3_f32 v133, v133, v108, v109
	v_max3_f32 v132, v132, v110, v111
	v_mfma_f32_32x32x16_bf16 v[16:31], v[162:165], v[196:199], v[16:31]
	ds_read_b128 v[48:51], v144 offset:8192
	ds_read_b128 v[52:55], v145 offset:8192
	ds_read_b128 v[56:59], v144 offset:12288
	ds_read_b128 v[60:63], v145 offset:12288
	v_max3_f32 v133, v133, v112, v113
	v_max3_f32 v132, v132, v114, v115
	v_max3_f32 v133, v133, v116, v117
	v_max3_f32 v132, v132, v118, v119
	v_max3_f32 v133, v133, v120, v121
	v_max3_f32 v132, v132, v122, v123
	v_max3_f32 v133, v133, v124, v125
	v_max3_f32 v132, v132, v126, v127
	v_max_f32_e32 v132, v132, v133
	s_cmp_lg_u32 s95, 0
	s_cbranch_scc1 .Lat_rareg0b
	v_cmp_lt_f32_e32 vcc, s4, v132
	s_cbranch_vccnz .Lat_rareg0b
.Lat_backg0b:
	v_exp_f32_e32 v96, v96
	v_exp_f32_e32 v97, v97
	v_exp_f32_e32 v98, v98
	v_exp_f32_e32 v99, v99
	v_exp_f32_e32 v100, v100
	v_exp_f32_e32 v101, v101
	v_exp_f32_e32 v102, v102
	v_exp_f32_e32 v103, v103
	v_cvt_pk_bf16_f32 v162, v96, v97
	v_cvt_pk_bf16_f32 v163, v98, v99
	v_cvt_pk_bf16_f32 v164, v100, v101
	v_cvt_pk_bf16_f32 v165, v102, v103
	v_pk_add_f32 v[130:131], v[130:131], v[96:97]
	v_pk_add_f32 v[130:131], v[130:131], v[98:99]
	v_pk_add_f32 v[130:131], v[130:131], v[100:101]
	v_pk_add_f32 v[130:131], v[130:131], v[102:103]
	v_mfma_f32_32x32x16_bf16 v[80:95], v[162:165], v[168:171], v[80:95]
	v_exp_f32_e32 v104, v104
	v_exp_f32_e32 v105, v105
	v_exp_f32_e32 v106, v106
	v_exp_f32_e32 v107, v107
	v_mfma_f32_32x32x16_bf16 v[200:215], v[162:165], v[172:175], v[200:215]
	v_exp_f32_e32 v108, v108
	v_exp_f32_e32 v109, v109
	v_exp_f32_e32 v110, v110
	v_exp_f32_e32 v111, v111
	v_cvt_pk_bf16_f32 v162, v104, v105
	v_cvt_pk_bf16_f32 v163, v106, v107
	v_cvt_pk_bf16_f32 v164, v108, v109
	v_cvt_pk_bf16_f32 v165, v110, v111
	v_pk_add_f32 v[130:131], v[130:131], v[104:105]
	v_pk_add_f32 v[130:131], v[130:131], v[106:107]
	v_pk_add_f32 v[130:131], v[130:131], v[108:109]
	v_pk_add_f32 v[130:131], v[130:131], v[110:111]
	v_mfma_f32_32x32x16_bf16 v[80:95], v[162:165], v[176:179], v[80:95]
	v_exp_f32_e32 v112, v112
	v_exp_f32_e32 v113, v113
	v_exp_f32_e32 v114, v114
	v_exp_f32_e32 v115, v115
	v_mfma_f32_32x32x16_bf16 v[200:215], v[162:165], v[180:183], v[200:215]
	v_exp_f32_e32 v116, v116
	v_exp_f32_e32 v117, v117
	v_exp_f32_e32 v118, v118
	v_exp_f32_e32 v119, v119
	v_cvt_pk_bf16_f32 v162, v112, v113
	v_cvt_pk_bf16_f32 v163, v114, v115
	v_cvt_pk_bf16_f32 v164, v116, v117
	v_cvt_pk_bf16_f32 v165, v118, v119
	v_pk_add_f32 v[130:131], v[130:131], v[112:113]
	v_pk_add_f32 v[130:131], v[130:131], v[114:115]
	v_pk_add_f32 v[130:131], v[130:131], v[116:117]
	v_pk_add_f32 v[130:131], v[130:131], v[118:119]
	v_mfma_f32_32x32x16_bf16 v[80:95], v[162:165], v[184:187], v[80:95]
	v_exp_f32_e32 v120, v120
	v_exp_f32_e32 v121, v121
	v_exp_f32_e32 v122, v122
	v_exp_f32_e32 v123, v123
	v_mfma_f32_32x32x16_bf16 v[200:215], v[162:165], v[188:191], v[200:215]
	v_exp_f32_e32 v124, v124
	v_exp_f32_e32 v125, v125
	v_exp_f32_e32 v126, v126
	v_exp_f32_e32 v127, v127
	v_cvt_pk_bf16_f32 v162, v120, v121
	v_cvt_pk_bf16_f32 v163, v122, v123
	v_cvt_pk_bf16_f32 v164, v124, v125
	v_cvt_pk_bf16_f32 v165, v126, v127
	v_pk_add_f32 v[130:131], v[130:131], v[120:121]
	v_pk_add_f32 v[130:131], v[130:131], v[122:123]
	v_pk_add_f32 v[130:131], v[130:131], v[124:125]
	v_pk_add_f32 v[130:131], v[130:131], v[126:127]
	v_mfma_f32_32x32x16_bf16 v[80:95], v[162:165], v[192:195], v[80:95]
	v_mfma_f32_32x32x16_bf16 v[200:215], v[162:165], v[196:199], v[200:215]
	s_waitcnt lgkmcnt(0)
	v_mfma_f32_32x32x16_bf16 v[96:111], v[48:51], v[136:139], v[32:47]
	ds_read_b64_tr_b16 v[168:169], v146 offset:8192
	ds_read_b64_tr_b16 v[170:171], v146 offset:9216
	ds_read_b64_tr_b16 v[172:173], v146 offset:8704
	ds_read_b64_tr_b16 v[174:175], v146 offset:9728
	v_mfma_f32_32x32x16_bf16 v[96:111], v[52:55], v[140:143], v[96:111]
	ds_read_b64_tr_b16 v[176:177], v146 offset:10240
	ds_read_b64_tr_b16 v[178:179], v146 offset:11264
	ds_read_b64_tr_b16 v[180:181], v146 offset:10752
	ds_read_b64_tr_b16 v[182:183], v146 offset:11776
	v_mfma_f32_32x32x16_bf16 v[112:127], v[56:59], v[136:139], v[32:47]
	ds_read_b64_tr_b16 v[184:185], v146 offset:12288
	ds_read_b64_tr_b16 v[186:187], v146 offset:13312
	ds_read_b64_tr_b16 v[188:189], v146 offset:12800
	ds_read_b64_tr_b16 v[190:191], v146 offset:13824
	v_mfma_f32_32x32x16_bf16 v[112:127], v[60:63], v[140:143], v[112:127]
	ds_read_b64_tr_b16 v[192:193], v146 offset:14336
	ds_read_b64_tr_b16 v[194:195], v146 offset:15360
	ds_read_b64_tr_b16 v[196:197], v146 offset:14848
	ds_read_b64_tr_b16 v[198:199], v146 offset:15872
	v_max3_f32 v132, v96, v97, v98
	v_max3_f32 v133, v99, v100, v101
	v_max3_f32 v132, v132, v102, v103
	v_max3_f32 v133, v133, v104, v105
	v_max3_f32 v132, v132, v106, v107
	v_max3_f32 v133, v133, v108, v109
	v_max3_f32 v132, v132, v110, v111
	s_nop 1
	v_max3_f32 v133, v133, v112, v113
	v_max3_f32 v132, v132, v114, v115
	v_max3_f32 v133, v133, v116, v117
	v_max3_f32 v132, v132, v118, v119
	v_max3_f32 v133, v133, v120, v121
	v_max3_f32 v132, v132, v122, v123
	v_max3_f32 v133, v133, v124, v125
	v_max3_f32 v132, v132, v126, v127
	v_max_f32_e32 v132, v132, v133
	v_cmp_lt_f32_e32 vcc, s4, v132
	s_cbranch_vccnz .Lat_rareg1a
.Lat_backg1a:
	v_exp_f32_e32 v96, v96
	v_exp_f32_e32 v97, v97
	v_exp_f32_e32 v98, v98
	v_exp_f32_e32 v99, v99
	v_exp_f32_e32 v100, v100
	v_exp_f32_e32 v101, v101
	v_exp_f32_e32 v102, v102
	v_exp_f32_e32 v103, v103
	v_cvt_pk_bf16_f32 v162, v96, v97
	v_cvt_pk_bf16_f32 v163, v98, v99
	v_cvt_pk_bf16_f32 v164, v100, v101
	v_cvt_pk_bf16_f32 v165, v102, v103
	v_pk_add_f32 v[128:129], v[128:129], v[96:97]
	v_pk_add_f32 v[128:129], v[128:129], v[98:99]
	v_pk_add_f32 v[128:129], v[128:129], v[100:101]
	v_pk_add_f32 v[128:129], v[128:129], v[102:103]
	s_waitcnt lgkmcnt(12)
	v_mfma_f32_32x32x16_bf16 v[0:15], v[162:165], v[168:171], v[0:15]
	v_exp_f32_e32 v104, v104
	v_exp_f32_e32 v105, v105
	v_exp_f32_e32 v106, v106
	v_exp_f32_e32 v107, v107
	v_mfma_f32_32x32x16_bf16 v[16:31], v[162:165], v[172:175], v[16:31]
	v_exp_f32_e32 v108, v108
	v_exp_f32_e32 v109, v109
	v_exp_f32_e32 v110, v110
	v_exp_f32_e32 v111, v111
	v_cvt_pk_bf16_f32 v162, v104, v105
	v_cvt_pk_bf16_f32 v163, v106, v107
	v_cvt_pk_bf16_f32 v164, v108, v109
	v_cvt_pk_bf16_f32 v165, v110, v111
	v_pk_add_f32 v[128:129], v[128:129], v[104:105]
	v_pk_add_f32 v[128:129], v[128:129], v[106:107]
	v_pk_add_f32 v[128:129], v[128:129], v[108:109]
	v_pk_add_f32 v[128:129], v[128:129], v[110:111]
	s_waitcnt lgkmcnt(8)
	v_mfma_f32_32x32x16_bf16 v[0:15], v[162:165], v[176:179], v[0:15]
	v_exp_f32_e32 v112, v112
	v_exp_f32_e32 v113, v113
	v_exp_f32_e32 v114, v114
	v_exp_f32_e32 v115, v115
	v_mfma_f32_32x32x16_bf16 v[16:31], v[162:165], v[180:183], v[16:31]
	v_mfma_f32_32x32x16_bf16 v[96:111], v[48:51], v[150:153], v[64:79]
	v_exp_f32_e32 v116, v116
	v_exp_f32_e32 v117, v117
	v_exp_f32_e32 v118, v118
	v_exp_f32_e32 v119, v119
	v_mfma_f32_32x32x16_bf16 v[96:111], v[52:55], v[154:157], v[96:111]
	v_cvt_pk_bf16_f32 v162, v112, v113
	v_cvt_pk_bf16_f32 v163, v114, v115
	v_cvt_pk_bf16_f32 v164, v116, v117
	v_cvt_pk_bf16_f32 v165, v118, v119
	v_pk_add_f32 v[128:129], v[128:129], v[112:113]
	v_pk_add_f32 v[128:129], v[128:129], v[114:115]
	v_pk_add_f32 v[128:129], v[128:129], v[116:117]
	v_pk_add_f32 v[128:129], v[128:129], v[118:119]
	s_waitcnt lgkmcnt(4)
	v_mfma_f32_32x32x16_bf16 v[0:15], v[162:165], v[184:187], v[0:15]
	v_exp_f32_e32 v120, v120
	v_exp_f32_e32 v121, v121
	v_exp_f32_e32 v122, v122
	v_exp_f32_e32 v123, v123
	v_mfma_f32_32x32x16_bf16 v[16:31], v[162:165], v[188:191], v[16:31]
	v_exp_f32_e32 v124, v124
	v_exp_f32_e32 v125, v125
	v_exp_f32_e32 v126, v126
	v_exp_f32_e32 v127, v127
	v_cvt_pk_bf16_f32 v162, v120, v121
	v_cvt_pk_bf16_f32 v163, v122, v123
	v_cvt_pk_bf16_f32 v164, v124, v125
	v_cvt_pk_bf16_f32 v165, v126, v127
	v_pk_add_f32 v[128:129], v[128:129], v[120:121]
	v_pk_add_f32 v[128:129], v[128:129], v[122:123]
	v_pk_add_f32 v[128:129], v[128:129], v[124:125]
	v_pk_add_f32 v[128:129], v[128:129], v[126:127]
	v_mfma_f32_32x32x16_bf16 v[112:127], v[56:59], v[150:153], v[64:79]
	v_mfma_f32_32x32x16_bf16 v[112:127], v[60:63], v[154:157], v[112:127]
	s_waitcnt lgkmcnt(0)
	v_mfma_f32_32x32x16_bf16 v[0:15], v[162:165], v[192:195], v[0:15]
	v_max3_f32 v132, v96, v97, v98
	v_max3_f32 v133, v99, v100, v101
	v_max3_f32 v132, v132, v102, v103
	v_max3_f32 v133, v133, v104, v105
	v_max3_f32 v132, v132, v106, v107
	v_max3_f32 v133, v133, v108, v109
	v_max3_f32 v132, v132, v110, v111
	v_mfma_f32_32x32x16_bf16 v[16:31], v[162:165], v[196:199], v[16:31]
	s_nop 2
	v_max3_f32 v133, v133, v112, v113
	v_max3_f32 v132, v132, v114, v115
	v_max3_f32 v133, v133, v116, v117
	v_max3_f32 v132, v132, v118, v119
	v_max3_f32 v133, v133, v120, v121
	v_max3_f32 v132, v132, v122, v123
	v_max3_f32 v133, v133, v124, v125
	v_max3_f32 v132, v132, v126, v127
	v_max_f32_e32 v132, v132, v133
	v_cmp_lt_f32_e32 vcc, s4, v132
	s_cbranch_vccnz .Lat_rareg1b

.Lat_ndg1:
	ds_read_b128 v[48:51], v144 offset:16384
	ds_read_b128 v[52:55], v145 offset:16384
	ds_read_b128 v[56:59], v144 offset:20480
	ds_read_b128 v[60:63], v145 offset:20480
	v_mfma_f32_32x32x16_bf16 v[80:95], v[162:165], v[192:195], v[80:95]
	v_mfma_f32_32x32x16_bf16 v[200:215], v[162:165], v[196:199], v[200:215]
	s_waitcnt lgkmcnt(0)
	v_mfma_f32_32x32x16_bf16 v[96:111], v[48:51], v[136:139], v[32:47]
	ds_read_b64_tr_b16 v[168:169], v146 offset:16384
	ds_read_b64_tr_b16 v[170:171], v146 offset:17408
	ds_read_b64_tr_b16 v[172:173], v146 offset:16896
	ds_read_b64_tr_b16 v[174:175], v146 offset:17920
	v_mfma_f32_32x32x16_bf16 v[96:111], v[52:55], v[140:143], v[96:111]
	ds_read_b64_tr_b16 v[176:177], v146 offset:18432
	ds_read_b64_tr_b16 v[178:179], v146 offset:19456
	ds_read_b64_tr_b16 v[180:181], v146 offset:18944
	ds_read_b64_tr_b16 v[182:183], v146 offset:19968
	v_mfma_f32_32x32x16_bf16 v[112:127], v[56:59], v[136:139], v[32:47]
	ds_read_b64_tr_b16 v[184:185], v146 offset:20480
	ds_read_b64_tr_b16 v[186:187], v146 offset:21504
	ds_read_b64_tr_b16 v[188:189], v146 offset:20992
	ds_read_b64_tr_b16 v[190:191], v146 offset:22016
	v_mfma_f32_32x32x16_bf16 v[112:127], v[60:63], v[140:143], v[112:127]
	ds_read_b64_tr_b16 v[192:193], v146 offset:22528
	ds_read_b64_tr_b16 v[194:195], v146 offset:23552
	ds_read_b64_tr_b16 v[196:197], v146 offset:23040
	ds_read_b64_tr_b16 v[198:199], v146 offset:24064
	v_max3_f32 v132, v96, v97, v98
	v_max3_f32 v133, v99, v100, v101
	v_max3_f32 v132, v132, v102, v103
	v_max3_f32 v133, v133, v104, v105
	v_max3_f32 v132, v132, v106, v107
	v_max3_f32 v133, v133, v108, v109
	v_max3_f32 v132, v132, v110, v111
	s_nop 1
	v_max3_f32 v133, v133, v112, v113
	v_max3_f32 v132, v132, v114, v115
	v_max3_f32 v133, v133, v116, v117
	v_max3_f32 v132, v132, v118, v119
	v_max3_f32 v133, v133, v120, v121
	v_max3_f32 v132, v132, v122, v123
	v_max3_f32 v133, v133, v124, v125
	v_max3_f32 v132, v132, v126, v127
	v_max_f32_e32 v132, v132, v133
	v_cmp_lt_f32_e32 vcc, s4, v132
	s_cbranch_vccnz .Lat_rareg2a
.Lat_backg2a:
	v_exp_f32_e32 v96, v96
	v_exp_f32_e32 v97, v97
	v_exp_f32_e32 v98, v98
	v_exp_f32_e32 v99, v99
	v_exp_f32_e32 v100, v100
	v_exp_f32_e32 v101, v101
	v_exp_f32_e32 v102, v102
	v_exp_f32_e32 v103, v103
	v_cvt_pk_bf16_f32 v162, v96, v97
	v_cvt_pk_bf16_f32 v163, v98, v99
	v_cvt_pk_bf16_f32 v164, v100, v101
	v_cvt_pk_bf16_f32 v165, v102, v103
	v_pk_add_f32 v[128:129], v[128:129], v[96:97]
	v_pk_add_f32 v[128:129], v[128:129], v[98:99]
	v_pk_add_f32 v[128:129], v[128:129], v[100:101]
	v_pk_add_f32 v[128:129], v[128:129], v[102:103]
	s_waitcnt lgkmcnt(12)
	v_mfma_f32_32x32x16_bf16 v[0:15], v[162:165], v[168:171], v[0:15]
	v_exp_f32_e32 v104, v104
	v_exp_f32_e32 v105, v105
	v_exp_f32_e32 v106, v106
	v_exp_f32_e32 v107, v107
	v_mfma_f32_32x32x16_bf16 v[16:31], v[162:165], v[172:175], v[16:31]
	v_exp_f32_e32 v108, v108
	v_exp_f32_e32 v109, v109
	v_exp_f32_e32 v110, v110
	v_exp_f32_e32 v111, v111
	v_cvt_pk_bf16_f32 v162, v104, v105
	v_cvt_pk_bf16_f32 v163, v106, v107
	v_cvt_pk_bf16_f32 v164, v108, v109
	v_cvt_pk_bf16_f32 v165, v110, v111
	v_pk_add_f32 v[128:129], v[128:129], v[104:105]
	v_pk_add_f32 v[128:129], v[128:129], v[106:107]
	v_pk_add_f32 v[128:129], v[128:129], v[108:109]
	v_pk_add_f32 v[128:129], v[128:129], v[110:111]
	s_waitcnt lgkmcnt(8)
	v_mfma_f32_32x32x16_bf16 v[0:15], v[162:165], v[176:179], v[0:15]
	v_exp_f32_e32 v112, v112
	v_exp_f32_e32 v113, v113
	v_exp_f32_e32 v114, v114
	v_exp_f32_e32 v115, v115
	v_mfma_f32_32x32x16_bf16 v[16:31], v[162:165], v[180:183], v[16:31]
	v_mfma_f32_32x32x16_bf16 v[96:111], v[48:51], v[150:153], v[64:79]
	v_exp_f32_e32 v116, v116
	v_exp_f32_e32 v117, v117
	v_exp_f32_e32 v118, v118
	v_exp_f32_e32 v119, v119
	v_mfma_f32_32x32x16_bf16 v[96:111], v[52:55], v[154:157], v[96:111]
	v_cvt_pk_bf16_f32 v162, v112, v113
	v_cvt_pk_bf16_f32 v163, v114, v115
	v_cvt_pk_bf16_f32 v164, v116, v117
	v_cvt_pk_bf16_f32 v165, v118, v119
	v_pk_add_f32 v[128:129], v[128:129], v[112:113]
	v_pk_add_f32 v[128:129], v[128:129], v[114:115]
	v_pk_add_f32 v[128:129], v[128:129], v[116:117]
	v_pk_add_f32 v[128:129], v[128:129], v[118:119]
	s_waitcnt lgkmcnt(4)
	v_mfma_f32_32x32x16_bf16 v[0:15], v[162:165], v[184:187], v[0:15]
	v_exp_f32_e32 v120, v120
	v_exp_f32_e32 v121, v121
	v_exp_f32_e32 v122, v122
	v_exp_f32_e32 v123, v123
	v_mfma_f32_32x32x16_bf16 v[16:31], v[162:165], v[188:191], v[16:31]
	v_exp_f32_e32 v124, v124
	v_exp_f32_e32 v125, v125
	v_exp_f32_e32 v126, v126
	v_exp_f32_e32 v127, v127
	v_cvt_pk_bf16_f32 v162, v120, v121
	v_cvt_pk_bf16_f32 v163, v122, v123
	v_cvt_pk_bf16_f32 v164, v124, v125
	v_cvt_pk_bf16_f32 v165, v126, v127
	v_pk_add_f32 v[128:129], v[128:129], v[120:121]
	v_pk_add_f32 v[128:129], v[128:129], v[122:123]
	v_pk_add_f32 v[128:129], v[128:129], v[124:125]
	v_pk_add_f32 v[128:129], v[128:129], v[126:127]
	v_mfma_f32_32x32x16_bf16 v[112:127], v[56:59], v[150:153], v[64:79]
	v_mfma_f32_32x32x16_bf16 v[112:127], v[60:63], v[154:157], v[112:127]
	s_waitcnt lgkmcnt(0)
	v_mfma_f32_32x32x16_bf16 v[0:15], v[162:165], v[192:195], v[0:15]
	v_max3_f32 v132, v96, v97, v98
	v_max3_f32 v133, v99, v100, v101
	v_max3_f32 v132, v132, v102, v103
	v_max3_f32 v133, v133, v104, v105
	v_max3_f32 v132, v132, v106, v107
	v_max3_f32 v133, v133, v108, v109
	v_max3_f32 v132, v132, v110, v111
	v_mfma_f32_32x32x16_bf16 v[16:31], v[162:165], v[196:199], v[16:31]
	ds_read_b128 v[48:51], v144 offset:24576
	ds_read_b128 v[52:55], v145 offset:24576
	ds_read_b128 v[56:59], v144 offset:28672
	ds_read_b128 v[60:63], v145 offset:28672
	v_max3_f32 v133, v133, v112, v113
	v_max3_f32 v132, v132, v114, v115
	v_max3_f32 v133, v133, v116, v117
	v_max3_f32 v132, v132, v118, v119
	v_max3_f32 v133, v133, v120, v121
	v_max3_f32 v132, v132, v122, v123
	v_max3_f32 v133, v133, v124, v125
	v_max3_f32 v132, v132, v126, v127
	v_max_f32_e32 v132, v132, v133
	v_cmp_lt_f32_e32 vcc, s4, v132
	s_cbranch_vccnz .Lat_rareg2b
.Lat_backg2b:
	v_exp_f32_e32 v96, v96
	v_exp_f32_e32 v97, v97
	v_exp_f32_e32 v98, v98
	v_exp_f32_e32 v99, v99
	v_exp_f32_e32 v100, v100
	v_exp_f32_e32 v101, v101
	v_exp_f32_e32 v102, v102
	v_exp_f32_e32 v103, v103
	v_cvt_pk_bf16_f32 v162, v96, v97
	v_cvt_pk_bf16_f32 v163, v98, v99
	v_cvt_pk_bf16_f32 v164, v100, v101
	v_cvt_pk_bf16_f32 v165, v102, v103
	v_pk_add_f32 v[130:131], v[130:131], v[96:97]
	v_pk_add_f32 v[130:131], v[130:131], v[98:99]
	v_pk_add_f32 v[130:131], v[130:131], v[100:101]
	v_pk_add_f32 v[130:131], v[130:131], v[102:103]
	v_mfma_f32_32x32x16_bf16 v[80:95], v[162:165], v[168:171], v[80:95]
	v_exp_f32_e32 v104, v104
	v_exp_f32_e32 v105, v105
	v_exp_f32_e32 v106, v106
	v_exp_f32_e32 v107, v107
	v_mfma_f32_32x32x16_bf16 v[200:215], v[162:165], v[172:175], v[200:215]
	v_exp_f32_e32 v108, v108
	v_exp_f32_e32 v109, v109
	v_exp_f32_e32 v110, v110
	v_exp_f32_e32 v111, v111
	v_cvt_pk_bf16_f32 v162, v104, v105
	v_cvt_pk_bf16_f32 v163, v106, v107
	v_cvt_pk_bf16_f32 v164, v108, v109
	v_cvt_pk_bf16_f32 v165, v110, v111
	v_pk_add_f32 v[130:131], v[130:131], v[104:105]
	v_pk_add_f32 v[130:131], v[130:131], v[106:107]
	v_pk_add_f32 v[130:131], v[130:131], v[108:109]
	v_pk_add_f32 v[130:131], v[130:131], v[110:111]
	v_mfma_f32_32x32x16_bf16 v[80:95], v[162:165], v[176:179], v[80:95]
	v_exp_f32_e32 v112, v112
	v_exp_f32_e32 v113, v113
	v_exp_f32_e32 v114, v114
	v_exp_f32_e32 v115, v115
	v_mfma_f32_32x32x16_bf16 v[200:215], v[162:165], v[180:183], v[200:215]
	v_exp_f32_e32 v116, v116
	v_exp_f32_e32 v117, v117
	v_exp_f32_e32 v118, v118
	v_exp_f32_e32 v119, v119
	v_cvt_pk_bf16_f32 v162, v112, v113
	v_cvt_pk_bf16_f32 v163, v114, v115
	v_cvt_pk_bf16_f32 v164, v116, v117
	v_cvt_pk_bf16_f32 v165, v118, v119
	v_pk_add_f32 v[130:131], v[130:131], v[112:113]
	v_pk_add_f32 v[130:131], v[130:131], v[114:115]
	v_pk_add_f32 v[130:131], v[130:131], v[116:117]
	v_pk_add_f32 v[130:131], v[130:131], v[118:119]
	v_mfma_f32_32x32x16_bf16 v[80:95], v[162:165], v[184:187], v[80:95]
	v_exp_f32_e32 v120, v120
	v_exp_f32_e32 v121, v121
	v_exp_f32_e32 v122, v122
	v_exp_f32_e32 v123, v123
	v_mfma_f32_32x32x16_bf16 v[200:215], v[162:165], v[188:191], v[200:215]
	v_exp_f32_e32 v124, v124
	v_exp_f32_e32 v125, v125
	v_exp_f32_e32 v126, v126
	v_exp_f32_e32 v127, v127
	v_cvt_pk_bf16_f32 v162, v120, v121
	v_cvt_pk_bf16_f32 v163, v122, v123
	v_cvt_pk_bf16_f32 v164, v124, v125
	v_cvt_pk_bf16_f32 v165, v126, v127
	v_pk_add_f32 v[130:131], v[130:131], v[120:121]
	v_pk_add_f32 v[130:131], v[130:131], v[122:123]
	v_pk_add_f32 v[130:131], v[130:131], v[124:125]
	v_pk_add_f32 v[130:131], v[130:131], v[126:127]
	v_mfma_f32_32x32x16_bf16 v[80:95], v[162:165], v[192:195], v[80:95]
	v_mfma_f32_32x32x16_bf16 v[200:215], v[162:165], v[196:199], v[200:215]
	s_waitcnt lgkmcnt(0)
	v_mfma_f32_32x32x16_bf16 v[96:111], v[48:51], v[136:139], v[32:47]
	ds_read_b64_tr_b16 v[168:169], v146 offset:24576
	ds_read_b64_tr_b16 v[170:171], v146 offset:25600
	ds_read_b64_tr_b16 v[172:173], v146 offset:25088
	ds_read_b64_tr_b16 v[174:175], v146 offset:26112
	v_mfma_f32_32x32x16_bf16 v[96:111], v[52:55], v[140:143], v[96:111]
	ds_read_b64_tr_b16 v[176:177], v146 offset:26624
	ds_read_b64_tr_b16 v[178:179], v146 offset:27648
	ds_read_b64_tr_b16 v[180:181], v146 offset:27136
	ds_read_b64_tr_b16 v[182:183], v146 offset:28160
	v_mfma_f32_32x32x16_bf16 v[112:127], v[56:59], v[136:139], v[32:47]
	ds_read_b64_tr_b16 v[184:185], v146 offset:28672
	ds_read_b64_tr_b16 v[186:187], v146 offset:29696
	ds_read_b64_tr_b16 v[188:189], v146 offset:29184
	ds_read_b64_tr_b16 v[190:191], v146 offset:30208
	v_mfma_f32_32x32x16_bf16 v[112:127], v[60:63], v[140:143], v[112:127]
	ds_read_b64_tr_b16 v[192:193], v146 offset:30720
	ds_read_b64_tr_b16 v[194:195], v146 offset:31744
	ds_read_b64_tr_b16 v[196:197], v146 offset:31232
	ds_read_b64_tr_b16 v[198:199], v146 offset:32256
	v_max3_f32 v132, v96, v97, v98
	v_max3_f32 v133, v99, v100, v101
	v_max3_f32 v132, v132, v102, v103
	v_max3_f32 v133, v133, v104, v105
	v_max3_f32 v132, v132, v106, v107
	v_max3_f32 v133, v133, v108, v109
	v_max3_f32 v132, v132, v110, v111
	s_nop 1
	v_max3_f32 v133, v133, v112, v113
	v_max3_f32 v132, v132, v114, v115
	v_max3_f32 v133, v133, v116, v117
	v_max3_f32 v132, v132, v118, v119
	v_max3_f32 v133, v133, v120, v121
	v_max3_f32 v132, v132, v122, v123
	v_max3_f32 v133, v133, v124, v125
	v_max3_f32 v132, v132, v126, v127
	v_max_f32_e32 v132, v132, v133
	v_cmp_lt_f32_e32 vcc, s4, v132
	s_cbranch_vccnz .Lat_rareg3a

.Lat_ndg3:
	ds_read_b128 v[48:51], v144 offset:32768
	ds_read_b128 v[52:55], v145 offset:32768
	ds_read_b128 v[56:59], v144 offset:36864
	ds_read_b128 v[60:63], v145 offset:36864
	v_mfma_f32_32x32x16_bf16 v[80:95], v[162:165], v[192:195], v[80:95]
	v_mfma_f32_32x32x16_bf16 v[200:215], v[162:165], v[196:199], v[200:215]
	s_waitcnt lgkmcnt(0)
	v_mfma_f32_32x32x16_bf16 v[96:111], v[48:51], v[136:139], v[32:47]
	ds_read_b64_tr_b16 v[168:169], v146 offset:32768
	ds_read_b64_tr_b16 v[170:171], v146 offset:33792
	ds_read_b64_tr_b16 v[172:173], v146 offset:33280
	ds_read_b64_tr_b16 v[174:175], v146 offset:34304
	v_mfma_f32_32x32x16_bf16 v[96:111], v[52:55], v[140:143], v[96:111]
	ds_read_b64_tr_b16 v[176:177], v146 offset:34816
	ds_read_b64_tr_b16 v[178:179], v146 offset:35840
	ds_read_b64_tr_b16 v[180:181], v146 offset:35328
	ds_read_b64_tr_b16 v[182:183], v146 offset:36352
	v_mfma_f32_32x32x16_bf16 v[112:127], v[56:59], v[136:139], v[32:47]
	ds_read_b64_tr_b16 v[184:185], v146 offset:36864
	ds_read_b64_tr_b16 v[186:187], v146 offset:37888
	ds_read_b64_tr_b16 v[188:189], v146 offset:37376
	ds_read_b64_tr_b16 v[190:191], v146 offset:38400
	v_mfma_f32_32x32x16_bf16 v[112:127], v[60:63], v[140:143], v[112:127]
	ds_read_b64_tr_b16 v[192:193], v146 offset:38912
	ds_read_b64_tr_b16 v[194:195], v146 offset:39936
	ds_read_b64_tr_b16 v[196:197], v146 offset:39424
	ds_read_b64_tr_b16 v[198:199], v146 offset:40448
	v_max3_f32 v132, v96, v97, v98
	v_max3_f32 v133, v99, v100, v101
	v_max3_f32 v132, v132, v102, v103
	v_max3_f32 v133, v133, v104, v105
	v_max3_f32 v132, v132, v106, v107
	v_max3_f32 v133, v133, v108, v109
	v_max3_f32 v132, v132, v110, v111
	s_nop 1
	v_max3_f32 v133, v133, v112, v113
	v_max3_f32 v132, v132, v114, v115
	v_max3_f32 v133, v133, v116, v117
	v_max3_f32 v132, v132, v118, v119
	v_max3_f32 v133, v133, v120, v121
	v_max3_f32 v132, v132, v122, v123
	v_max3_f32 v133, v133, v124, v125
	v_max3_f32 v132, v132, v126, v127
	v_max_f32_e32 v132, v132, v133
	v_cmp_lt_f32_e32 vcc, s4, v132
	s_cbranch_vccnz .Lat_rareg4a
.Lat_backg4a:
	v_exp_f32_e32 v96, v96
	v_exp_f32_e32 v97, v97
	v_exp_f32_e32 v98, v98
	v_exp_f32_e32 v99, v99
	v_exp_f32_e32 v100, v100
	v_exp_f32_e32 v101, v101
	v_exp_f32_e32 v102, v102
	v_exp_f32_e32 v103, v103
	v_cvt_pk_bf16_f32 v162, v96, v97
	v_cvt_pk_bf16_f32 v163, v98, v99
	v_cvt_pk_bf16_f32 v164, v100, v101
	v_cvt_pk_bf16_f32 v165, v102, v103
	v_pk_add_f32 v[128:129], v[128:129], v[96:97]
	v_pk_add_f32 v[128:129], v[128:129], v[98:99]
	v_pk_add_f32 v[128:129], v[128:129], v[100:101]
	v_pk_add_f32 v[128:129], v[128:129], v[102:103]
	s_waitcnt lgkmcnt(12)
	v_mfma_f32_32x32x16_bf16 v[0:15], v[162:165], v[168:171], v[0:15]
	v_exp_f32_e32 v104, v104
	v_exp_f32_e32 v105, v105
	v_exp_f32_e32 v106, v106
	v_exp_f32_e32 v107, v107
	v_mfma_f32_32x32x16_bf16 v[16:31], v[162:165], v[172:175], v[16:31]
	v_exp_f32_e32 v108, v108
	v_exp_f32_e32 v109, v109
	v_exp_f32_e32 v110, v110
	v_exp_f32_e32 v111, v111
	v_cvt_pk_bf16_f32 v162, v104, v105
	v_cvt_pk_bf16_f32 v163, v106, v107
	v_cvt_pk_bf16_f32 v164, v108, v109
	v_cvt_pk_bf16_f32 v165, v110, v111
	v_pk_add_f32 v[128:129], v[128:129], v[104:105]
	v_pk_add_f32 v[128:129], v[128:129], v[106:107]
	v_pk_add_f32 v[128:129], v[128:129], v[108:109]
	v_pk_add_f32 v[128:129], v[128:129], v[110:111]
	s_waitcnt lgkmcnt(8)
	v_mfma_f32_32x32x16_bf16 v[0:15], v[162:165], v[176:179], v[0:15]
	v_exp_f32_e32 v112, v112
	v_exp_f32_e32 v113, v113
	v_exp_f32_e32 v114, v114
	v_exp_f32_e32 v115, v115
	v_mfma_f32_32x32x16_bf16 v[16:31], v[162:165], v[180:183], v[16:31]
	v_mfma_f32_32x32x16_bf16 v[96:111], v[48:51], v[150:153], v[64:79]
	v_exp_f32_e32 v116, v116
	v_exp_f32_e32 v117, v117
	v_exp_f32_e32 v118, v118
	v_exp_f32_e32 v119, v119
	v_mfma_f32_32x32x16_bf16 v[96:111], v[52:55], v[154:157], v[96:111]
	v_cvt_pk_bf16_f32 v162, v112, v113
	v_cvt_pk_bf16_f32 v163, v114, v115
	v_cvt_pk_bf16_f32 v164, v116, v117
	v_cvt_pk_bf16_f32 v165, v118, v119
	v_pk_add_f32 v[128:129], v[128:129], v[112:113]
	v_pk_add_f32 v[128:129], v[128:129], v[114:115]
	v_pk_add_f32 v[128:129], v[128:129], v[116:117]
	v_pk_add_f32 v[128:129], v[128:129], v[118:119]
	s_waitcnt lgkmcnt(4)
	v_mfma_f32_32x32x16_bf16 v[0:15], v[162:165], v[184:187], v[0:15]
	v_exp_f32_e32 v120, v120
	v_exp_f32_e32 v121, v121
	v_exp_f32_e32 v122, v122
	v_exp_f32_e32 v123, v123
	v_mfma_f32_32x32x16_bf16 v[16:31], v[162:165], v[188:191], v[16:31]
	v_exp_f32_e32 v124, v124
	v_exp_f32_e32 v125, v125
	v_exp_f32_e32 v126, v126
	v_exp_f32_e32 v127, v127
	v_cvt_pk_bf16_f32 v162, v120, v121
	v_cvt_pk_bf16_f32 v163, v122, v123
	v_cvt_pk_bf16_f32 v164, v124, v125
	v_cvt_pk_bf16_f32 v165, v126, v127
	v_pk_add_f32 v[128:129], v[128:129], v[120:121]
	v_pk_add_f32 v[128:129], v[128:129], v[122:123]
	v_pk_add_f32 v[128:129], v[128:129], v[124:125]
	v_pk_add_f32 v[128:129], v[128:129], v[126:127]
	v_mfma_f32_32x32x16_bf16 v[112:127], v[56:59], v[150:153], v[64:79]
	v_mfma_f32_32x32x16_bf16 v[112:127], v[60:63], v[154:157], v[112:127]
	s_waitcnt lgkmcnt(0)
	v_mfma_f32_32x32x16_bf16 v[0:15], v[162:165], v[192:195], v[0:15]
	v_max3_f32 v132, v96, v97, v98
	v_max3_f32 v133, v99, v100, v101
	v_max3_f32 v132, v132, v102, v103
	v_max3_f32 v133, v133, v104, v105
	v_max3_f32 v132, v132, v106, v107
	v_max3_f32 v133, v133, v108, v109
	v_max3_f32 v132, v132, v110, v111
	v_mfma_f32_32x32x16_bf16 v[16:31], v[162:165], v[196:199], v[16:31]
	ds_read_b128 v[48:51], v144 offset:40960
	ds_read_b128 v[52:55], v145 offset:40960
	ds_read_b128 v[56:59], v144 offset:45056
	ds_read_b128 v[60:63], v145 offset:45056
	v_max3_f32 v133, v133, v112, v113
	v_max3_f32 v132, v132, v114, v115
	v_max3_f32 v133, v133, v116, v117
	v_max3_f32 v132, v132, v118, v119
	v_max3_f32 v133, v133, v120, v121
	v_max3_f32 v132, v132, v122, v123
	v_max3_f32 v133, v133, v124, v125
	v_max3_f32 v132, v132, v126, v127
	v_max_f32_e32 v132, v132, v133
	v_cmp_lt_f32_e32 vcc, s4, v132
	s_cbranch_vccnz .Lat_rareg4b
.Lat_backg4b:
	v_exp_f32_e32 v96, v96
	v_exp_f32_e32 v97, v97
	v_exp_f32_e32 v98, v98
	v_exp_f32_e32 v99, v99
	v_exp_f32_e32 v100, v100
	v_exp_f32_e32 v101, v101
	v_exp_f32_e32 v102, v102
	v_exp_f32_e32 v103, v103
	v_cvt_pk_bf16_f32 v162, v96, v97
	v_cvt_pk_bf16_f32 v163, v98, v99
	v_cvt_pk_bf16_f32 v164, v100, v101
	v_cvt_pk_bf16_f32 v165, v102, v103
	v_pk_add_f32 v[130:131], v[130:131], v[96:97]
	v_pk_add_f32 v[130:131], v[130:131], v[98:99]
	v_pk_add_f32 v[130:131], v[130:131], v[100:101]
	v_pk_add_f32 v[130:131], v[130:131], v[102:103]
	v_mfma_f32_32x32x16_bf16 v[80:95], v[162:165], v[168:171], v[80:95]
	v_exp_f32_e32 v104, v104
	v_exp_f32_e32 v105, v105
	v_exp_f32_e32 v106, v106
	v_exp_f32_e32 v107, v107
	v_mfma_f32_32x32x16_bf16 v[200:215], v[162:165], v[172:175], v[200:215]
	v_exp_f32_e32 v108, v108
	v_exp_f32_e32 v109, v109
	v_exp_f32_e32 v110, v110
	v_exp_f32_e32 v111, v111
	v_cvt_pk_bf16_f32 v162, v104, v105
	v_cvt_pk_bf16_f32 v163, v106, v107
	v_cvt_pk_bf16_f32 v164, v108, v109
	v_cvt_pk_bf16_f32 v165, v110, v111
	v_pk_add_f32 v[130:131], v[130:131], v[104:105]
	v_pk_add_f32 v[130:131], v[130:131], v[106:107]
	v_pk_add_f32 v[130:131], v[130:131], v[108:109]
	v_pk_add_f32 v[130:131], v[130:131], v[110:111]
	v_mfma_f32_32x32x16_bf16 v[80:95], v[162:165], v[176:179], v[80:95]
	v_exp_f32_e32 v112, v112
	v_exp_f32_e32 v113, v113
	v_exp_f32_e32 v114, v114
	v_exp_f32_e32 v115, v115
	v_mfma_f32_32x32x16_bf16 v[200:215], v[162:165], v[180:183], v[200:215]
	v_exp_f32_e32 v116, v116
	v_exp_f32_e32 v117, v117
	v_exp_f32_e32 v118, v118
	v_exp_f32_e32 v119, v119
	v_cvt_pk_bf16_f32 v162, v112, v113
	v_cvt_pk_bf16_f32 v163, v114, v115
	v_cvt_pk_bf16_f32 v164, v116, v117
	v_cvt_pk_bf16_f32 v165, v118, v119
	v_pk_add_f32 v[130:131], v[130:131], v[112:113]
	v_pk_add_f32 v[130:131], v[130:131], v[114:115]
	v_pk_add_f32 v[130:131], v[130:131], v[116:117]
	v_pk_add_f32 v[130:131], v[130:131], v[118:119]
	v_mfma_f32_32x32x16_bf16 v[80:95], v[162:165], v[184:187], v[80:95]
	v_exp_f32_e32 v120, v120
	v_exp_f32_e32 v121, v121
	v_exp_f32_e32 v122, v122
	v_exp_f32_e32 v123, v123
	v_mfma_f32_32x32x16_bf16 v[200:215], v[162:165], v[188:191], v[200:215]
	v_exp_f32_e32 v124, v124
	v_exp_f32_e32 v125, v125
	v_exp_f32_e32 v126, v126
	v_exp_f32_e32 v127, v127
	v_cvt_pk_bf16_f32 v162, v120, v121
	v_cvt_pk_bf16_f32 v163, v122, v123
	v_cvt_pk_bf16_f32 v164, v124, v125
	v_cvt_pk_bf16_f32 v165, v126, v127
	v_pk_add_f32 v[130:131], v[130:131], v[120:121]
	v_pk_add_f32 v[130:131], v[130:131], v[122:123]
	v_pk_add_f32 v[130:131], v[130:131], v[124:125]
	v_pk_add_f32 v[130:131], v[130:131], v[126:127]
	v_mfma_f32_32x32x16_bf16 v[80:95], v[162:165], v[192:195], v[80:95]
	v_mfma_f32_32x32x16_bf16 v[200:215], v[162:165], v[196:199], v[200:215]
	s_waitcnt lgkmcnt(0)
	v_mfma_f32_32x32x16_bf16 v[96:111], v[48:51], v[136:139], v[32:47]
	ds_read_b64_tr_b16 v[168:169], v146 offset:40960
	ds_read_b64_tr_b16 v[170:171], v146 offset:41984
	ds_read_b64_tr_b16 v[172:173], v146 offset:41472
	ds_read_b64_tr_b16 v[174:175], v146 offset:42496
	v_mfma_f32_32x32x16_bf16 v[96:111], v[52:55], v[140:143], v[96:111]
	ds_read_b64_tr_b16 v[176:177], v146 offset:43008
	ds_read_b64_tr_b16 v[178:179], v146 offset:44032
	ds_read_b64_tr_b16 v[180:181], v146 offset:43520
	ds_read_b64_tr_b16 v[182:183], v146 offset:44544
	v_mfma_f32_32x32x16_bf16 v[112:127], v[56:59], v[136:139], v[32:47]
	ds_read_b64_tr_b16 v[184:185], v146 offset:45056
	ds_read_b64_tr_b16 v[186:187], v146 offset:46080
	ds_read_b64_tr_b16 v[188:189], v146 offset:45568
	ds_read_b64_tr_b16 v[190:191], v146 offset:46592
	v_mfma_f32_32x32x16_bf16 v[112:127], v[60:63], v[140:143], v[112:127]
	ds_read_b64_tr_b16 v[192:193], v146 offset:47104
	ds_read_b64_tr_b16 v[194:195], v146 offset:48128
	ds_read_b64_tr_b16 v[196:197], v146 offset:47616
	ds_read_b64_tr_b16 v[198:199], v146 offset:48640
	v_max3_f32 v132, v96, v97, v98
	v_max3_f32 v133, v99, v100, v101
	v_max3_f32 v132, v132, v102, v103
	v_max3_f32 v133, v133, v104, v105
	v_max3_f32 v132, v132, v106, v107
	v_max3_f32 v133, v133, v108, v109
	v_max3_f32 v132, v132, v110, v111
	s_nop 1
	v_max3_f32 v133, v133, v112, v113
	v_max3_f32 v132, v132, v114, v115
	v_max3_f32 v133, v133, v116, v117
	v_max3_f32 v132, v132, v118, v119
	v_max3_f32 v133, v133, v120, v121
	v_max3_f32 v132, v132, v122, v123
	v_max3_f32 v133, v133, v124, v125
	v_max3_f32 v132, v132, v126, v127
	v_max_f32_e32 v132, v132, v133
	v_cmp_lt_f32_e32 vcc, s4, v132
	s_cbranch_vccnz .Lat_rareg5a

.Lat_rareg0a:
	v_mov_b32_e32 v133, v132
	s_nop 1
	v_permlane32_swap_b32_e32 v132, v133
	v_max_f32_e32 v132, v132, v133
	s_cmp_lg_u32 s94, 0
	s_cbranch_scc1 .Lat_firsta
	v_max_f32_e32 v132, 0, v132
	v_exp_f32_e64 v133, -v132
	v_add_f32_e32 v234, v234, v132
	s_nop 0
	ds_write_b32 v148, v133
	v_mul_f32_e32 v128, v128, v133
	v_mul_f32_e32 v129, v129, v133
	v_sub_f32_e32 v96, v96, v132
	v_sub_f32_e32 v97, v97, v132
	v_sub_f32_e32 v98, v98, v132
	v_sub_f32_e32 v99, v99, v132
	v_sub_f32_e32 v100, v100, v132
	v_sub_f32_e32 v101, v101, v132
	v_sub_f32_e32 v102, v102, v132
	v_sub_f32_e32 v103, v103, v132
	v_sub_f32_e32 v104, v104, v132
	v_sub_f32_e32 v105, v105, v132
	v_sub_f32_e32 v106, v106, v132
	v_sub_f32_e32 v107, v107, v132
	v_sub_f32_e32 v108, v108, v132
	v_sub_f32_e32 v109, v109, v132
	v_sub_f32_e32 v110, v110, v132
	v_sub_f32_e32 v111, v111, v132
	v_sub_f32_e32 v112, v112, v132
	v_sub_f32_e32 v113, v113, v132
	v_sub_f32_e32 v114, v114, v132
	v_sub_f32_e32 v115, v115, v132
	v_sub_f32_e32 v116, v116, v132
	v_sub_f32_e32 v117, v117, v132
	v_sub_f32_e32 v118, v118, v132
	v_sub_f32_e32 v119, v119, v132
	v_sub_f32_e32 v120, v120, v132
	v_sub_f32_e32 v121, v121, v132
	v_sub_f32_e32 v122, v122, v132
	v_sub_f32_e32 v123, v123, v132
	v_sub_f32_e32 v124, v124, v132
	v_sub_f32_e32 v125, v125, v132
	v_sub_f32_e32 v126, v126, v132
	v_sub_f32_e32 v127, v127, v132
	v_xor_b32_e32 v32, 0x80000000, v234
	v_mov_b32_e32 v33, v32
	v_mov_b32_e32 v34, v32
	v_mov_b32_e32 v35, v32
	v_mov_b32_e32 v36, v32
	v_mov_b32_e32 v37, v32
	v_mov_b32_e32 v38, v32
	v_mov_b32_e32 v39, v32
	v_mov_b32_e32 v40, v32
	v_mov_b32_e32 v41, v32
	v_mov_b32_e32 v42, v32
	v_mov_b32_e32 v43, v32
	v_mov_b32_e32 v44, v32
	v_mov_b32_e32 v45, v32
	v_mov_b32_e32 v46, v32
	v_mov_b32_e32 v47, v32
	s_waitcnt lgkmcnt(0)
	ds_read_b128 v[162:165], v147 offset:0
	s_waitcnt lgkmcnt(0)
	v_mul_f32_e32 v0, v0, v162
	v_mul_f32_e32 v16, v16, v162
	v_mul_f32_e32 v1, v1, v163
	v_mul_f32_e32 v17, v17, v163
	v_mul_f32_e32 v2, v2, v164
	v_mul_f32_e32 v18, v18, v164
	v_mul_f32_e32 v3, v3, v165
	v_mul_f32_e32 v19, v19, v165
	ds_read_b128 v[162:165], v147 offset:32
	s_waitcnt lgkmcnt(0)
	v_mul_f32_e32 v4, v4, v162
	v_mul_f32_e32 v20, v20, v162
	v_mul_f32_e32 v5, v5, v163
	v_mul_f32_e32 v21, v21, v163
	v_mul_f32_e32 v6, v6, v164
	v_mul_f32_e32 v22, v22, v164
	v_mul_f32_e32 v7, v7, v165
	v_mul_f32_e32 v23, v23, v165
	ds_read_b128 v[162:165], v147 offset:64
	s_waitcnt lgkmcnt(0)
	v_mul_f32_e32 v8, v8, v162
	v_mul_f32_e32 v24, v24, v162
	v_mul_f32_e32 v9, v9, v163
	v_mul_f32_e32 v25, v25, v163
	v_mul_f32_e32 v10, v10, v164
	v_mul_f32_e32 v26, v26, v164
	v_mul_f32_e32 v11, v11, v165
	v_mul_f32_e32 v27, v27, v165
	ds_read_b128 v[162:165], v147 offset:96
	s_waitcnt lgkmcnt(0)
	v_mul_f32_e32 v12, v12, v162
	v_mul_f32_e32 v28, v28, v162
	v_mul_f32_e32 v13, v13, v163
	v_mul_f32_e32 v29, v29, v163
	v_mul_f32_e32 v14, v14, v164
	v_mul_f32_e32 v30, v30, v164
	v_mul_f32_e32 v15, v15, v165
	v_mul_f32_e32 v31, v31, v165
	s_branch .Lat_backg0a

.Lat_rareg0b:
	v_mov_b32_e32 v133, v132
	s_nop 1
	v_permlane32_swap_b32_e32 v132, v133
	v_max_f32_e32 v132, v132, v133
	s_cmp_lg_u32 s95, 0
	s_cbranch_scc1 .Lat_firstb
	v_max_f32_e32 v132, 0, v132
	v_exp_f32_e64 v133, -v132
	v_add_f32_e32 v149, v149, v132
	s_nop 0
	ds_write_b32 v148, v133
	v_mul_f32_e32 v130, v130, v133
	v_mul_f32_e32 v131, v131, v133
	v_sub_f32_e32 v96, v96, v132
	v_sub_f32_e32 v97, v97, v132
	v_sub_f32_e32 v98, v98, v132
	v_sub_f32_e32 v99, v99, v132
	v_sub_f32_e32 v100, v100, v132
	v_sub_f32_e32 v101, v101, v132
	v_sub_f32_e32 v102, v102, v132
	v_sub_f32_e32 v103, v103, v132
	v_sub_f32_e32 v104, v104, v132
	v_sub_f32_e32 v105, v105, v132
	v_sub_f32_e32 v106, v106, v132
	v_sub_f32_e32 v107, v107, v132
	v_sub_f32_e32 v108, v108, v132
	v_sub_f32_e32 v109, v109, v132
	v_sub_f32_e32 v110, v110, v132
	v_sub_f32_e32 v111, v111, v132
	v_sub_f32_e32 v112, v112, v132
	v_sub_f32_e32 v113, v113, v132
	v_sub_f32_e32 v114, v114, v132
	v_sub_f32_e32 v115, v115, v132
	v_sub_f32_e32 v116, v116, v132
	v_sub_f32_e32 v117, v117, v132
	v_sub_f32_e32 v118, v118, v132
	v_sub_f32_e32 v119, v119, v132
	v_sub_f32_e32 v120, v120, v132
	v_sub_f32_e32 v121, v121, v132
	v_sub_f32_e32 v122, v122, v132
	v_sub_f32_e32 v123, v123, v132
	v_sub_f32_e32 v124, v124, v132
	v_sub_f32_e32 v125, v125, v132
	v_sub_f32_e32 v126, v126, v132
	v_sub_f32_e32 v127, v127, v132
	v_xor_b32_e32 v64, 0x80000000, v149
	v_mov_b32_e32 v65, v64
	v_mov_b32_e32 v66, v64
	v_mov_b32_e32 v67, v64
	v_mov_b32_e32 v68, v64
	v_mov_b32_e32 v69, v64
	v_mov_b32_e32 v70, v64
	v_mov_b32_e32 v71, v64
	v_mov_b32_e32 v72, v64
	v_mov_b32_e32 v73, v64
	v_mov_b32_e32 v74, v64
	v_mov_b32_e32 v75, v64
	v_mov_b32_e32 v76, v64
	v_mov_b32_e32 v77, v64
	v_mov_b32_e32 v78, v64
	v_mov_b32_e32 v79, v64
	s_waitcnt lgkmcnt(0)
	ds_read_b128 v[162:165], v147 offset:0
	s_waitcnt lgkmcnt(0)
	v_mul_f32_e32 v80, v80, v162
	v_mul_f32_e32 v200, v200, v162
	v_mul_f32_e32 v81, v81, v163
	v_mul_f32_e32 v201, v201, v163
	v_mul_f32_e32 v82, v82, v164
	v_mul_f32_e32 v202, v202, v164
	v_mul_f32_e32 v83, v83, v165
	v_mul_f32_e32 v203, v203, v165
	ds_read_b128 v[162:165], v147 offset:32
	s_waitcnt lgkmcnt(0)
	v_mul_f32_e32 v84, v84, v162
	v_mul_f32_e32 v204, v204, v162
	v_mul_f32_e32 v85, v85, v163
	v_mul_f32_e32 v205, v205, v163
	v_mul_f32_e32 v86, v86, v164
	v_mul_f32_e32 v206, v206, v164
	v_mul_f32_e32 v87, v87, v165
	v_mul_f32_e32 v207, v207, v165
	ds_read_b128 v[162:165], v147 offset:64
	s_waitcnt lgkmcnt(0)
	v_mul_f32_e32 v88, v88, v162
	v_mul_f32_e32 v208, v208, v162
	v_mul_f32_e32 v89, v89, v163
	v_mul_f32_e32 v209, v209, v163
	v_mul_f32_e32 v90, v90, v164
	v_mul_f32_e32 v210, v210, v164
	v_mul_f32_e32 v91, v91, v165
	v_mul_f32_e32 v211, v211, v165
	ds_read_b128 v[162:165], v147 offset:96
	s_waitcnt lgkmcnt(0)
	v_mul_f32_e32 v92, v92, v162
	v_mul_f32_e32 v212, v212, v162
	v_mul_f32_e32 v93, v93, v163
	v_mul_f32_e32 v213, v213, v163
	v_mul_f32_e32 v94, v94, v164
	v_mul_f32_e32 v214, v214, v164
	v_mul_f32_e32 v95, v95, v165
	v_mul_f32_e32 v215, v215, v165
	s_branch .Lat_backg0b

.Lat_rareg1a:
	v_mov_b32_e32 v133, v132
	s_nop 1
	v_permlane32_swap_b32_e32 v132, v133
	v_max_f32_e32 v132, v132, v133
	v_max_f32_e32 v132, 0, v132
	v_exp_f32_e64 v133, -v132
	v_add_f32_e32 v234, v234, v132
	s_nop 0
	ds_write_b32 v148, v133
	v_mul_f32_e32 v128, v128, v133
	v_mul_f32_e32 v129, v129, v133
	v_sub_f32_e32 v96, v96, v132
	v_sub_f32_e32 v97, v97, v132
	v_sub_f32_e32 v98, v98, v132
	v_sub_f32_e32 v99, v99, v132
	v_sub_f32_e32 v100, v100, v132
	v_sub_f32_e32 v101, v101, v132
	v_sub_f32_e32 v102, v102, v132
	v_sub_f32_e32 v103, v103, v132
	v_sub_f32_e32 v104, v104, v132
	v_sub_f32_e32 v105, v105, v132
	v_sub_f32_e32 v106, v106, v132
	v_sub_f32_e32 v107, v107, v132
	v_sub_f32_e32 v108, v108, v132
	v_sub_f32_e32 v109, v109, v132
	v_sub_f32_e32 v110, v110, v132
	v_sub_f32_e32 v111, v111, v132
	v_sub_f32_e32 v112, v112, v132
	v_sub_f32_e32 v113, v113, v132
	v_sub_f32_e32 v114, v114, v132
	v_sub_f32_e32 v115, v115, v132
	v_sub_f32_e32 v116, v116, v132
	v_sub_f32_e32 v117, v117, v132
	v_sub_f32_e32 v118, v118, v132
	v_sub_f32_e32 v119, v119, v132
	v_sub_f32_e32 v120, v120, v132
	v_sub_f32_e32 v121, v121, v132
	v_sub_f32_e32 v122, v122, v132
	v_sub_f32_e32 v123, v123, v132
	v_sub_f32_e32 v124, v124, v132
	v_sub_f32_e32 v125, v125, v132
	v_sub_f32_e32 v126, v126, v132
	v_sub_f32_e32 v127, v127, v132
	v_xor_b32_e32 v32, 0x80000000, v234
	v_mov_b32_e32 v33, v32
	v_mov_b32_e32 v34, v32
	v_mov_b32_e32 v35, v32
	v_mov_b32_e32 v36, v32
	v_mov_b32_e32 v37, v32
	v_mov_b32_e32 v38, v32
	v_mov_b32_e32 v39, v32
	v_mov_b32_e32 v40, v32
	v_mov_b32_e32 v41, v32
	v_mov_b32_e32 v42, v32
	v_mov_b32_e32 v43, v32
	v_mov_b32_e32 v44, v32
	v_mov_b32_e32 v45, v32
	v_mov_b32_e32 v46, v32
	v_mov_b32_e32 v47, v32
	s_waitcnt lgkmcnt(0)
	ds_read_b128 v[162:165], v147 offset:0
	s_waitcnt lgkmcnt(0)
	v_mul_f32_e32 v0, v0, v162
	v_mul_f32_e32 v16, v16, v162
	v_mul_f32_e32 v1, v1, v163
	v_mul_f32_e32 v17, v17, v163
	v_mul_f32_e32 v2, v2, v164
	v_mul_f32_e32 v18, v18, v164
	v_mul_f32_e32 v3, v3, v165
	v_mul_f32_e32 v19, v19, v165
	ds_read_b128 v[162:165], v147 offset:32
	s_waitcnt lgkmcnt(0)
	v_mul_f32_e32 v4, v4, v162
	v_mul_f32_e32 v20, v20, v162
	v_mul_f32_e32 v5, v5, v163
	v_mul_f32_e32 v21, v21, v163
	v_mul_f32_e32 v6, v6, v164
	v_mul_f32_e32 v22, v22, v164
	v_mul_f32_e32 v7, v7, v165
	v_mul_f32_e32 v23, v23, v165
	ds_read_b128 v[162:165], v147 offset:64
	s_waitcnt lgkmcnt(0)
	v_mul_f32_e32 v8, v8, v162
	v_mul_f32_e32 v24, v24, v162
	v_mul_f32_e32 v9, v9, v163
	v_mul_f32_e32 v25, v25, v163
	v_mul_f32_e32 v10, v10, v164
	v_mul_f32_e32 v26, v26, v164
	v_mul_f32_e32 v11, v11, v165
	v_mul_f32_e32 v27, v27, v165
	ds_read_b128 v[162:165], v147 offset:96
	s_waitcnt lgkmcnt(0)
	v_mul_f32_e32 v12, v12, v162
	v_mul_f32_e32 v28, v28, v162
	v_mul_f32_e32 v13, v13, v163
	v_mul_f32_e32 v29, v29, v163
	v_mul_f32_e32 v14, v14, v164
	v_mul_f32_e32 v30, v30, v164
	v_mul_f32_e32 v15, v15, v165
	v_mul_f32_e32 v31, v31, v165
	s_branch .Lat_backg1a
.Lat_rareg1b:
	v_mov_b32_e32 v133, v132
	s_nop 1
	v_permlane32_swap_b32_e32 v132, v133
	v_max_f32_e32 v132, v132, v133
	v_max_f32_e32 v132, 0, v132
	v_exp_f32_e64 v133, -v132
	v_add_f32_e32 v149, v149, v132
	s_nop 0
	ds_write_b32 v148, v133
	v_mul_f32_e32 v130, v130, v133
	v_mul_f32_e32 v131, v131, v133
	v_sub_f32_e32 v96, v96, v132
	v_sub_f32_e32 v97, v97, v132
	v_sub_f32_e32 v98, v98, v132
	v_sub_f32_e32 v99, v99, v132
	v_sub_f32_e32 v100, v100, v132
	v_sub_f32_e32 v101, v101, v132
	v_sub_f32_e32 v102, v102, v132
	v_sub_f32_e32 v103, v103, v132
	v_sub_f32_e32 v104, v104, v132
	v_sub_f32_e32 v105, v105, v132
	v_sub_f32_e32 v106, v106, v132
	v_sub_f32_e32 v107, v107, v132
	v_sub_f32_e32 v108, v108, v132
	v_sub_f32_e32 v109, v109, v132
	v_sub_f32_e32 v110, v110, v132
	v_sub_f32_e32 v111, v111, v132
	v_sub_f32_e32 v112, v112, v132
	v_sub_f32_e32 v113, v113, v132
	v_sub_f32_e32 v114, v114, v132
	v_sub_f32_e32 v115, v115, v132
	v_sub_f32_e32 v116, v116, v132
	v_sub_f32_e32 v117, v117, v132
	v_sub_f32_e32 v118, v118, v132
	v_sub_f32_e32 v119, v119, v132
	v_sub_f32_e32 v120, v120, v132
	v_sub_f32_e32 v121, v121, v132
	v_sub_f32_e32 v122, v122, v132
	v_sub_f32_e32 v123, v123, v132
	v_sub_f32_e32 v124, v124, v132
	v_sub_f32_e32 v125, v125, v132
	v_sub_f32_e32 v126, v126, v132
	v_sub_f32_e32 v127, v127, v132
	v_xor_b32_e32 v64, 0x80000000, v149
	v_mov_b32_e32 v65, v64
	v_mov_b32_e32 v66, v64
	v_mov_b32_e32 v67, v64
	v_mov_b32_e32 v68, v64
	v_mov_b32_e32 v69, v64
	v_mov_b32_e32 v70, v64
	v_mov_b32_e32 v71, v64
	v_mov_b32_e32 v72, v64
	v_mov_b32_e32 v73, v64
	v_mov_b32_e32 v74, v64
	v_mov_b32_e32 v75, v64
	v_mov_b32_e32 v76, v64
	v_mov_b32_e32 v77, v64
	v_mov_b32_e32 v78, v64
	v_mov_b32_e32 v79, v64
	s_waitcnt lgkmcnt(0)
	ds_read_b128 v[162:165], v147 offset:0
	s_waitcnt lgkmcnt(0)
	v_mul_f32_e32 v80, v80, v162
	v_mul_f32_e32 v200, v200, v162
	v_mul_f32_e32 v81, v81, v163
	v_mul_f32_e32 v201, v201, v163
	v_mul_f32_e32 v82, v82, v164
	v_mul_f32_e32 v202, v202, v164
	v_mul_f32_e32 v83, v83, v165
	v_mul_f32_e32 v203, v203, v165
	ds_read_b128 v[162:165], v147 offset:32
	s_waitcnt lgkmcnt(0)
	v_mul_f32_e32 v84, v84, v162
	v_mul_f32_e32 v204, v204, v162
	v_mul_f32_e32 v85, v85, v163
	v_mul_f32_e32 v205, v205, v163
	v_mul_f32_e32 v86, v86, v164
	v_mul_f32_e32 v206, v206, v164
	v_mul_f32_e32 v87, v87, v165
	v_mul_f32_e32 v207, v207, v165
	ds_read_b128 v[162:165], v147 offset:64
	s_waitcnt lgkmcnt(0)
	v_mul_f32_e32 v88, v88, v162
	v_mul_f32_e32 v208, v208, v162
	v_mul_f32_e32 v89, v89, v163
	v_mul_f32_e32 v209, v209, v163
	v_mul_f32_e32 v90, v90, v164
	v_mul_f32_e32 v210, v210, v164
	v_mul_f32_e32 v91, v91, v165
	v_mul_f32_e32 v211, v211, v165
	ds_read_b128 v[162:165], v147 offset:96
	s_waitcnt lgkmcnt(0)
	v_mul_f32_e32 v92, v92, v162
	v_mul_f32_e32 v212, v212, v162
	v_mul_f32_e32 v93, v93, v163
	v_mul_f32_e32 v213, v213, v163
	v_mul_f32_e32 v94, v94, v164
	v_mul_f32_e32 v214, v214, v164
	v_mul_f32_e32 v95, v95, v165
	v_mul_f32_e32 v215, v215, v165
	s_branch .Lat_backg1b
